# K-loop LDS-DMA loads use SGPR base + 32-bit VGPR offset (56 v_lshl_add_u64 removed from load segments); snake MFMA order
# speedup vs baseline: 1.0203x; 1.0203x over previous
; template <class Epi, class Sched, bool ALIGN_EPI = false, bool SP2 = false>
; __device__ __forceinline__ void gemm_phase(PG8_LAS unsigned char* lds, const Gemm g, const Sched& S, const Epi& E) {
;     ...
;             const char* a1 = cA + kstepA; const char* a2 = cA + 2 * kstepA; const char* b2 = cB + 2 * kstepB; const char* a3 = a2 + kstepA; const char* b3 = b2 + kstepB;
;             PG8_ITER(8);
;         }
;         for (int t = (Epi::PEEL ? 2 : 0); t < nt; t += 2) {
;             const bool last = (t == nt - 2);
;             const char* a1 = cA + (size_t)(t + 1) * kstepA;
;             const char* a2 = last ? nA : cA + (size_t)(t + 2) * kstepA; const char* b2 = last ? nB : cB + (size_t)(t + 2) * kstepB;
;             const char* a3 = a2 + kstepA; const char* b3 = b2 + kstepB;
.LBB0_161:
	ds_read_b128 v[146:149], v142
	ds_read_b128 v[150:153], v142 offset:1024
	ds_read_b128 v[154:157], v142 offset:2048
	ds_read_b128 v[162:165], v142 offset:3072
	ds_read_b128 v[166:169], v143
	ds_read_b128 v[170:173], v143 offset:1024
	ds_read_b128 v[174:177], v143 offset:2048
	ds_read_b128 v[180:183], v143 offset:3072
	s_add_u32 s8, s0, 0x3fc000
	s_addc_u32 s9, s1, 0
	s_cmp_eq_u32 s18, 12
	s_cselect_b32 s28, s44, s8
	s_cselect_b32 s29, s27, s9
	s_cselect_b32 s42, s49, s3
	s_cselect_b32 s43, s45, s2
	s_add_u32 s24, s28, 0x400000
	s_addc_u32 s25, s29, 0
	s_mov_b32 m0, s50
	ds_read_b128 v[184:187], v161
	ds_read_b128 v[188:191], v161 offset:1024
	ds_read_b128 v[192:195], v161 offset:2048
	ds_read_b128 v[196:199], v161 offset:3072
	ds_read_b128 v[200:203], v161 offset:4096
	ds_read_b128 v[204:207], v161 offset:5120
	ds_read_b128 v[208:211], v161 offset:6144
	ds_read_b128 v[212:215], v161 offset:7168
	global_load_lds_dwordx4 v140, s[0:1]
	s_mov_b32 m0, s51
	s_nop 0
	global_load_lds_dwordx4 v138, s[0:1]
	s_waitcnt vmcnt(8)
	s_waitcnt lgkmcnt(0)
	s_barrier
	s_setprio 1
	s_waitcnt lgkmcnt(0)
	v_mfma_f32_16x16x32_bf16 v[126:129], v[146:149], v[184:187], v[126:129]
	v_mfma_f32_16x16x32_bf16 v[118:121], v[154:157], v[184:187], v[118:121]
	v_mfma_f32_16x16x32_bf16 v[102:105], v[154:157], v[192:195], v[102:105]
	v_mfma_f32_16x16x32_bf16 v[110:113], v[146:149], v[192:195], v[110:113]
	v_mfma_f32_16x16x32_bf16 v[92:95], v[146:149], v[200:203], v[92:95]
	v_mfma_f32_16x16x32_bf16 v[84:87], v[154:157], v[200:203], v[84:87]
	v_mfma_f32_16x16x32_bf16 v[68:71], v[154:157], v[208:211], v[68:71]
	v_mfma_f32_16x16x32_bf16 v[76:79], v[146:149], v[208:211], v[76:79]
	v_mfma_f32_16x16x32_bf16 v[126:129], v[150:153], v[188:191], v[126:129]
	v_mfma_f32_16x16x32_bf16 v[118:121], v[162:165], v[188:191], v[118:121]
	v_mfma_f32_16x16x32_bf16 v[102:105], v[162:165], v[196:199], v[102:105]
	v_mfma_f32_16x16x32_bf16 v[110:113], v[150:153], v[196:199], v[110:113]
	v_mfma_f32_16x16x32_bf16 v[92:95], v[150:153], v[204:207], v[92:95]
	v_mfma_f32_16x16x32_bf16 v[84:87], v[162:165], v[204:207], v[84:87]
	v_mfma_f32_16x16x32_bf16 v[68:71], v[162:165], v[212:215], v[68:71]
	v_mfma_f32_16x16x32_bf16 v[76:79], v[150:153], v[212:215], v[76:79]
	s_setprio 0
	s_setprio 1
	v_mfma_f32_16x16x32_bf16 v[122:125], v[166:169], v[184:187], v[122:125]
	v_mfma_f32_16x16x32_bf16 v[114:117], v[174:177], v[184:187], v[114:117]
	v_mfma_f32_16x16x32_bf16 v[98:101], v[174:177], v[192:195], v[98:101]
	v_mfma_f32_16x16x32_bf16 v[106:109], v[166:169], v[192:195], v[106:109]
	v_mfma_f32_16x16x32_bf16 v[88:91], v[166:169], v[200:203], v[88:91]
	v_mfma_f32_16x16x32_bf16 v[80:83], v[174:177], v[200:203], v[80:83]
	v_mfma_f32_16x16x32_bf16 v[64:67], v[174:177], v[208:211], v[64:67]
	v_mfma_f32_16x16x32_bf16 v[72:75], v[166:169], v[208:211], v[72:75]
	v_mfma_f32_16x16x32_bf16 v[122:125], v[170:173], v[188:191], v[122:125]
	v_mfma_f32_16x16x32_bf16 v[114:117], v[180:183], v[188:191], v[114:117]
	v_mfma_f32_16x16x32_bf16 v[98:101], v[180:183], v[196:199], v[98:101]
	v_mfma_f32_16x16x32_bf16 v[106:109], v[170:173], v[196:199], v[106:109]
	v_mfma_f32_16x16x32_bf16 v[88:91], v[170:173], v[204:207], v[88:91]
	v_mfma_f32_16x16x32_bf16 v[80:83], v[180:183], v[204:207], v[80:83]
	v_mfma_f32_16x16x32_bf16 v[64:67], v[180:183], v[212:215], v[64:67]
	v_mfma_f32_16x16x32_bf16 v[72:75], v[170:173], v[212:215], v[72:75]
	s_setprio 0
	s_barrier
	s_mov_b32 m0, s55
	s_add_u32 s8, s42, 0x40000
	ds_read_b128 v[184:187], v161 offset:16384
	ds_read_b128 v[188:191], v161 offset:17408
	ds_read_b128 v[192:195], v161 offset:18432
	ds_read_b128 v[196:199], v161 offset:19456
	ds_read_b128 v[200:203], v161 offset:20480
	ds_read_b128 v[204:207], v161 offset:21504
	ds_read_b128 v[208:211], v161 offset:22528
	ds_read_b128 v[212:215], v161 offset:23552
	global_load_lds_dwordx4 v132, s[42:43]
	s_mov_b32 m0, vcc_lo
	s_addc_u32 s9, s43, 0
	global_load_lds_dwordx4 v136, s[42:43]
	s_mov_b32 m0, vcc_hi
	s_nop 0
	global_load_lds_dwordx4 v132, s[8:9]
	s_mov_b32 m0, s56
	s_nop 0
	global_load_lds_dwordx4 v136, s[8:9]
	s_mov_b32 m0, s22
	s_nop 0
	global_load_lds_dwordx4 v130, s[28:29]
	s_mov_b32 m0, s23
	s_nop 0
	global_load_lds_dwordx4 v134, s[28:29]
	s_waitcnt vmcnt(8)
	s_waitcnt lgkmcnt(0)
	s_barrier
	s_setprio 1
	s_waitcnt lgkmcnt(0)
	v_mfma_f32_16x16x32_bf16 v[60:63], v[146:149], v[184:187], v[60:63]
	v_mfma_f32_16x16x32_bf16 v[52:55], v[154:157], v[184:187], v[52:55]
	v_mfma_f32_16x16x32_bf16 v[36:39], v[154:157], v[192:195], v[36:39]
	v_mfma_f32_16x16x32_bf16 v[44:47], v[146:149], v[192:195], v[44:47]
	v_mfma_f32_16x16x32_bf16 v[28:31], v[146:149], v[200:203], v[28:31]
	v_mfma_f32_16x16x32_bf16 v[20:23], v[154:157], v[200:203], v[20:23]
	v_mfma_f32_16x16x32_bf16 v[4:7], v[154:157], v[208:211], v[4:7]
	v_mfma_f32_16x16x32_bf16 v[12:15], v[146:149], v[208:211], v[12:15]
	v_mfma_f32_16x16x32_bf16 v[60:63], v[150:153], v[188:191], v[60:63]
	v_mfma_f32_16x16x32_bf16 v[52:55], v[162:165], v[188:191], v[52:55]
	v_mfma_f32_16x16x32_bf16 v[36:39], v[162:165], v[196:199], v[36:39]
	v_mfma_f32_16x16x32_bf16 v[44:47], v[150:153], v[196:199], v[44:47]
	v_mfma_f32_16x16x32_bf16 v[28:31], v[150:153], v[204:207], v[28:31]
	v_mfma_f32_16x16x32_bf16 v[20:23], v[162:165], v[204:207], v[20:23]
	v_mfma_f32_16x16x32_bf16 v[4:7], v[162:165], v[212:215], v[4:7]
	v_mfma_f32_16x16x32_bf16 v[12:15], v[150:153], v[212:215], v[12:15]
	s_setprio 0
	s_setprio 1
	v_mfma_f32_16x16x32_bf16 v[56:59], v[166:169], v[184:187], v[56:59]
	v_mfma_f32_16x16x32_bf16 v[48:51], v[174:177], v[184:187], v[48:51]
	v_mfma_f32_16x16x32_bf16 v[32:35], v[174:177], v[192:195], v[32:35]
	v_mfma_f32_16x16x32_bf16 v[40:43], v[166:169], v[192:195], v[40:43]
	v_mfma_f32_16x16x32_bf16 v[24:27], v[166:169], v[200:203], v[24:27]
	v_mfma_f32_16x16x32_bf16 v[16:19], v[174:177], v[200:203], v[16:19]
	v_mfma_f32_16x16x32_bf16 v[0:3], v[174:177], v[208:211], v[0:3]
	v_mfma_f32_16x16x32_bf16 v[8:11], v[166:169], v[208:211], v[8:11]
	v_mfma_f32_16x16x32_bf16 v[56:59], v[170:173], v[188:191], v[56:59]
	v_mfma_f32_16x16x32_bf16 v[48:51], v[180:183], v[188:191], v[48:51]
	v_mfma_f32_16x16x32_bf16 v[32:35], v[180:183], v[196:199], v[32:35]
	v_mfma_f32_16x16x32_bf16 v[40:43], v[170:173], v[196:199], v[40:43]
	v_mfma_f32_16x16x32_bf16 v[24:27], v[170:173], v[204:207], v[24:27]
	v_mfma_f32_16x16x32_bf16 v[16:19], v[180:183], v[204:207], v[16:19]
	v_mfma_f32_16x16x32_bf16 v[0:3], v[180:183], v[212:215], v[0:3]
	v_mfma_f32_16x16x32_bf16 v[8:11], v[170:173], v[212:215], v[8:11]
	s_setprio 0
	s_barrier
; template <class Epi, class Sched, bool ALIGN_EPI = false, bool SP2 = false>
; __device__ __forceinline__ void gemm_phase(PG8_LAS unsigned char* lds, const Gemm g, const Sched& S, const Epi& E) {
;     ...
;         for (int t = (Epi::PEEL ? 2 : 0); t < nt; t += 2) {
;             const bool last = (t == nt - 2);
;             const char* a1 = cA + (size_t)(t + 1) * kstepA;
;             const char* a2 = last ? nA : cA + (size_t)(t + 2) * kstepA; const char* b2 = last ? nB : cB + (size_t)(t + 2) * kstepB;
;             const char* a3 = a2 + kstepA; const char* b3 = b2 + kstepB;
;             PG8_ITER(8);
	ds_read_b128 v[146:149], v144
	ds_read_b128 v[150:153], v144 offset:1024
	ds_read_b128 v[154:157], v144 offset:2048
	ds_read_b128 v[162:165], v144 offset:3072
	ds_read_b128 v[166:169], v145
	ds_read_b128 v[170:173], v145 offset:1024
	ds_read_b128 v[174:177], v145 offset:2048
	ds_read_b128 v[180:183], v145 offset:3072
	s_add_u32 s8, s28, 0x4000
	s_addc_u32 s9, s29, 0
	s_mov_b32 m0, s39
	ds_read_b128 v[184:187], v161 offset:32768
	ds_read_b128 v[188:191], v161 offset:33792
	ds_read_b128 v[192:195], v161 offset:34816
	ds_read_b128 v[196:199], v161 offset:35840
	ds_read_b128 v[200:203], v161 offset:36864
	ds_read_b128 v[204:207], v161 offset:37888
	ds_read_b128 v[208:211], v161 offset:38912
	ds_read_b128 v[212:215], v161 offset:39936
	global_load_lds_dwordx4 v130, s[8:9]
	s_mov_b32 m0, s52
	s_nop 0
	global_load_lds_dwordx4 v134, s[8:9]
	s_waitcnt vmcnt(8)
	s_waitcnt lgkmcnt(0)
	s_barrier
	s_setprio 1
	s_waitcnt lgkmcnt(0)
	v_mfma_f32_16x16x32_bf16 v[126:129], v[146:149], v[184:187], v[126:129]
	v_mfma_f32_16x16x32_bf16 v[118:121], v[154:157], v[184:187], v[118:121]
	v_mfma_f32_16x16x32_bf16 v[102:105], v[154:157], v[192:195], v[102:105]
	v_mfma_f32_16x16x32_bf16 v[110:113], v[146:149], v[192:195], v[110:113]
	v_mfma_f32_16x16x32_bf16 v[92:95], v[146:149], v[200:203], v[92:95]
	v_mfma_f32_16x16x32_bf16 v[84:87], v[154:157], v[200:203], v[84:87]
	v_mfma_f32_16x16x32_bf16 v[68:71], v[154:157], v[208:211], v[68:71]
	v_mfma_f32_16x16x32_bf16 v[76:79], v[146:149], v[208:211], v[76:79]
	v_mfma_f32_16x16x32_bf16 v[126:129], v[150:153], v[188:191], v[126:129]
	v_mfma_f32_16x16x32_bf16 v[118:121], v[162:165], v[188:191], v[118:121]
	v_mfma_f32_16x16x32_bf16 v[102:105], v[162:165], v[196:199], v[102:105]
	v_mfma_f32_16x16x32_bf16 v[110:113], v[150:153], v[196:199], v[110:113]
	v_mfma_f32_16x16x32_bf16 v[92:95], v[150:153], v[204:207], v[92:95]
	v_mfma_f32_16x16x32_bf16 v[84:87], v[162:165], v[204:207], v[84:87]
	v_mfma_f32_16x16x32_bf16 v[68:71], v[162:165], v[212:215], v[68:71]
	v_mfma_f32_16x16x32_bf16 v[76:79], v[150:153], v[212:215], v[76:79]
	s_setprio 0
	s_setprio 1
	v_mfma_f32_16x16x32_bf16 v[122:125], v[166:169], v[184:187], v[122:125]
	v_mfma_f32_16x16x32_bf16 v[114:117], v[174:177], v[184:187], v[114:117]
	v_mfma_f32_16x16x32_bf16 v[98:101], v[174:177], v[192:195], v[98:101]
	v_mfma_f32_16x16x32_bf16 v[106:109], v[166:169], v[192:195], v[106:109]
	v_mfma_f32_16x16x32_bf16 v[88:91], v[166:169], v[200:203], v[88:91]
	v_mfma_f32_16x16x32_bf16 v[80:83], v[174:177], v[200:203], v[80:83]
	v_mfma_f32_16x16x32_bf16 v[64:67], v[174:177], v[208:211], v[64:67]
	v_mfma_f32_16x16x32_bf16 v[72:75], v[166:169], v[208:211], v[72:75]
	v_mfma_f32_16x16x32_bf16 v[122:125], v[170:173], v[188:191], v[122:125]
	v_mfma_f32_16x16x32_bf16 v[114:117], v[180:183], v[188:191], v[114:117]
	v_mfma_f32_16x16x32_bf16 v[98:101], v[180:183], v[196:199], v[98:101]
	v_mfma_f32_16x16x32_bf16 v[106:109], v[170:173], v[196:199], v[106:109]
	v_mfma_f32_16x16x32_bf16 v[88:91], v[170:173], v[204:207], v[88:91]
	v_mfma_f32_16x16x32_bf16 v[80:83], v[180:183], v[204:207], v[80:83]
	v_mfma_f32_16x16x32_bf16 v[64:67], v[180:183], v[212:215], v[64:67]
	v_mfma_f32_16x16x32_bf16 v[72:75], v[170:173], v[212:215], v[72:75]
	s_setprio 0
	s_barrier
	s_mov_b32 m0, s30
	s_add_u32 s100, s42, 0x80
	s_addc_u32 s101, s43, 0
	s_add_u32 s8, s42, 0x40080
	ds_read_b128 v[184:187], v161 offset:49152
	ds_read_b128 v[188:191], v161 offset:50176
	ds_read_b128 v[192:195], v161 offset:51200
	ds_read_b128 v[196:199], v161 offset:52224
	ds_read_b128 v[200:203], v161 offset:53248
	ds_read_b128 v[204:207], v161 offset:54272
	ds_read_b128 v[208:211], v161 offset:55296
	ds_read_b128 v[212:215], v161 offset:56320
	global_load_lds_dwordx4 v132, s[100:101]
	s_mov_b32 m0, s31
	s_addc_u32 s9, s43, 0
	global_load_lds_dwordx4 v136, s[100:101]
	s_mov_b32 m0, s57
	s_nop 0
	global_load_lds_dwordx4 v132, s[8:9]
	s_mov_b32 m0, s96
	s_nop 0
	global_load_lds_dwordx4 v136, s[8:9]
	s_mov_b32 m0, s11
	s_nop 0
	global_load_lds_dwordx4 v130, s[24:25]
	s_mov_b32 m0, s19
	s_nop 0
	global_load_lds_dwordx4 v134, s[24:25]
	s_waitcnt vmcnt(8)
	s_waitcnt lgkmcnt(0)
	s_barrier
	s_setprio 1
	s_waitcnt lgkmcnt(0)
	v_mfma_f32_16x16x32_bf16 v[60:63], v[146:149], v[184:187], v[60:63]
	v_mfma_f32_16x16x32_bf16 v[52:55], v[154:157], v[184:187], v[52:55]
	v_mfma_f32_16x16x32_bf16 v[36:39], v[154:157], v[192:195], v[36:39]
	v_mfma_f32_16x16x32_bf16 v[44:47], v[146:149], v[192:195], v[44:47]
	v_mfma_f32_16x16x32_bf16 v[28:31], v[146:149], v[200:203], v[28:31]
	v_mfma_f32_16x16x32_bf16 v[20:23], v[154:157], v[200:203], v[20:23]
	v_mfma_f32_16x16x32_bf16 v[4:7], v[154:157], v[208:211], v[4:7]
	v_mfma_f32_16x16x32_bf16 v[12:15], v[146:149], v[208:211], v[12:15]
	v_mfma_f32_16x16x32_bf16 v[60:63], v[150:153], v[188:191], v[60:63]
	v_mfma_f32_16x16x32_bf16 v[52:55], v[162:165], v[188:191], v[52:55]
	v_mfma_f32_16x16x32_bf16 v[36:39], v[162:165], v[196:199], v[36:39]
	v_mfma_f32_16x16x32_bf16 v[44:47], v[150:153], v[196:199], v[44:47]
	v_mfma_f32_16x16x32_bf16 v[28:31], v[150:153], v[204:207], v[28:31]
	v_mfma_f32_16x16x32_bf16 v[20:23], v[162:165], v[204:207], v[20:23]
	v_mfma_f32_16x16x32_bf16 v[4:7], v[162:165], v[212:215], v[4:7]
	v_mfma_f32_16x16x32_bf16 v[12:15], v[150:153], v[212:215], v[12:15]
	s_setprio 0
	s_setprio 1
	v_mfma_f32_16x16x32_bf16 v[56:59], v[166:169], v[184:187], v[56:59]
	v_mfma_f32_16x16x32_bf16 v[48:51], v[174:177], v[184:187], v[48:51]
	v_mfma_f32_16x16x32_bf16 v[32:35], v[174:177], v[192:195], v[32:35]
	v_mfma_f32_16x16x32_bf16 v[40:43], v[166:169], v[192:195], v[40:43]
	v_mfma_f32_16x16x32_bf16 v[24:27], v[166:169], v[200:203], v[24:27]
	v_mfma_f32_16x16x32_bf16 v[16:19], v[174:177], v[200:203], v[16:19]
	v_mfma_f32_16x16x32_bf16 v[0:3], v[174:177], v[208:211], v[0:3]
	v_mfma_f32_16x16x32_bf16 v[8:11], v[166:169], v[208:211], v[8:11]
	v_mfma_f32_16x16x32_bf16 v[56:59], v[170:173], v[188:191], v[56:59]
	v_mfma_f32_16x16x32_bf16 v[48:51], v[180:183], v[188:191], v[48:51]
	v_mfma_f32_16x16x32_bf16 v[32:35], v[180:183], v[196:199], v[32:35]
	v_mfma_f32_16x16x32_bf16 v[40:43], v[170:173], v[196:199], v[40:43]
	v_mfma_f32_16x16x32_bf16 v[24:27], v[170:173], v[204:207], v[24:27]
	v_mfma_f32_16x16x32_bf16 v[16:19], v[180:183], v[204:207], v[16:19]
	v_mfma_f32_16x16x32_bf16 v[0:3], v[180:183], v[212:215], v[0:3]
	v_mfma_f32_16x16x32_bf16 v[8:11], v[170:173], v[212:215], v[8:11]
	s_setprio 0
	s_barrier
	s_add_i32 s18, s18, 2
	s_add_u32 s3, s3, 0x100
	s_addc_u32 s2, s2, 0
	s_add_u32 s0, s0, 0x800000
	s_addc_u32 s1, s1, 0
	s_cmp_gt_u32 s18, 13
	s_cbranch_scc0 .LBB0_161
	v_readlane_b32 s0, v255, 45
	v_readlane_b32 s1, v255, 46
	s_and_b64 vcc, exec, s[0:1]
	s_cbranch_vccz .LBB0_164
	s_barrier

; template <class Epi, class Sched, bool ALIGN_EPI = false, bool SP2 = false>
; __device__ __forceinline__ void gemm_phase(PG8_LAS unsigned char* lds, const Gemm g, const Sched& S, const Epi& E) {
;     ...
;             const char* a1 = cA + kstepA; const char* a2 = cA + 2 * kstepA; const char* b2 = cB + 2 * kstepB; const char* a3 = a2 + kstepA; const char* b3 = b2 + kstepB;
;             PG8_ITER(8);
;         }
;         for (int t = (Epi::PEEL ? 2 : 0); t < nt; t += 2) {
;             const bool last = (t == nt - 2);
;             const char* a1 = cA + (size_t)(t + 1) * kstepA;
;             const char* a2 = last ? nA : cA + (size_t)(t + 2) * kstepA; const char* b2 = last ? nB : cB + (size_t)(t + 2) * kstepB;
;             const char* a3 = a2 + kstepA; const char* b3 = b2 + kstepB;
.LBB0_250:
	ds_read_b128 v[146:149], v130
	ds_read_b128 v[152:155], v130 offset:1024
	ds_read_b128 v[156:159], v130 offset:2048
	ds_read_b128 v[160:163], v130 offset:3072
	ds_read_b128 v[164:167], v131
	ds_read_b128 v[168:171], v131 offset:1024
	ds_read_b128 v[172:175], v131 offset:2048
	ds_read_b128 v[180:183], v131 offset:3072
	s_add_u32 s16, s24, 0x3fc000
	s_addc_u32 s17, s25, 0
	s_cmp_eq_u32 s18, 12
	s_cselect_b32 s28, s47, s16
	s_cselect_b32 s29, s27, s17
	s_cselect_b32 s44, s54, s3
	s_cselect_b32 s45, s49, s2
	s_add_u32 s42, s28, 0x400000
	s_addc_u32 s43, s29, 0
	s_mov_b32 m0, s55
	ds_read_b128 v[184:187], v151
	ds_read_b128 v[188:191], v151 offset:1024
	ds_read_b128 v[192:195], v151 offset:2048
	ds_read_b128 v[196:199], v151 offset:3072
	ds_read_b128 v[200:203], v151 offset:4096
	ds_read_b128 v[204:207], v151 offset:5120
	ds_read_b128 v[208:211], v151 offset:6144
	ds_read_b128 v[212:215], v151 offset:7168
	global_load_lds_dwordx4 v144, s[24:25]
	s_mov_b32 m0, s98
	s_nop 0
	global_load_lds_dwordx4 v142, s[24:25]
	s_waitcnt vmcnt(8)
	s_waitcnt lgkmcnt(0)
	s_barrier
	s_setprio 1
	s_waitcnt lgkmcnt(0)
	v_mfma_f32_16x16x32_bf16 v[118:121], v[146:149], v[184:187], v[118:121]
	v_mfma_f32_16x16x32_bf16 v[114:117], v[156:159], v[184:187], v[114:117]
	v_mfma_f32_16x16x32_bf16 v[98:101], v[156:159], v[192:195], v[98:101]
	v_mfma_f32_16x16x32_bf16 v[102:105], v[146:149], v[192:195], v[102:105]
	v_mfma_f32_16x16x32_bf16 v[84:87], v[146:149], v[200:203], v[84:87]
	v_mfma_f32_16x16x32_bf16 v[80:83], v[156:159], v[200:203], v[80:83]
	v_mfma_f32_16x16x32_bf16 v[64:67], v[156:159], v[208:211], v[64:67]
	v_mfma_f32_16x16x32_bf16 v[68:71], v[146:149], v[208:211], v[68:71]
	v_mfma_f32_16x16x32_bf16 v[118:121], v[152:155], v[188:191], v[118:121]
	v_mfma_f32_16x16x32_bf16 v[114:117], v[160:163], v[188:191], v[114:117]
	v_mfma_f32_16x16x32_bf16 v[98:101], v[160:163], v[196:199], v[98:101]
	v_mfma_f32_16x16x32_bf16 v[102:105], v[152:155], v[196:199], v[102:105]
	v_mfma_f32_16x16x32_bf16 v[84:87], v[152:155], v[204:207], v[84:87]
	v_mfma_f32_16x16x32_bf16 v[80:83], v[160:163], v[204:207], v[80:83]
	v_mfma_f32_16x16x32_bf16 v[64:67], v[160:163], v[212:215], v[64:67]
	v_mfma_f32_16x16x32_bf16 v[68:71], v[152:155], v[212:215], v[68:71]
	s_setprio 0
	s_setprio 1
	v_mfma_f32_16x16x32_bf16 v[126:129], v[164:167], v[184:187], v[126:129]
	v_mfma_f32_16x16x32_bf16 v[122:125], v[172:175], v[184:187], v[122:125]
	v_mfma_f32_16x16x32_bf16 v[106:109], v[172:175], v[192:195], v[106:109]
	v_mfma_f32_16x16x32_bf16 v[110:113], v[164:167], v[192:195], v[110:113]
	v_mfma_f32_16x16x32_bf16 v[92:95], v[164:167], v[200:203], v[92:95]
	v_mfma_f32_16x16x32_bf16 v[88:91], v[172:175], v[200:203], v[88:91]
	v_mfma_f32_16x16x32_bf16 v[72:75], v[172:175], v[208:211], v[72:75]
	v_mfma_f32_16x16x32_bf16 v[76:79], v[164:167], v[208:211], v[76:79]
	v_mfma_f32_16x16x32_bf16 v[126:129], v[168:171], v[188:191], v[126:129]
	v_mfma_f32_16x16x32_bf16 v[122:125], v[180:183], v[188:191], v[122:125]
	v_mfma_f32_16x16x32_bf16 v[106:109], v[180:183], v[196:199], v[106:109]
	v_mfma_f32_16x16x32_bf16 v[110:113], v[168:171], v[196:199], v[110:113]
	v_mfma_f32_16x16x32_bf16 v[92:95], v[168:171], v[204:207], v[92:95]
	v_mfma_f32_16x16x32_bf16 v[88:91], v[180:183], v[204:207], v[88:91]
	v_mfma_f32_16x16x32_bf16 v[72:75], v[180:183], v[212:215], v[72:75]
	v_mfma_f32_16x16x32_bf16 v[76:79], v[168:171], v[212:215], v[76:79]
	s_setprio 0
	s_barrier
	s_mov_b32 m0, s99
	s_add_u32 s16, s44, 0x40000
	ds_read_b128 v[184:187], v151 offset:16384
	ds_read_b128 v[188:191], v151 offset:17408
	ds_read_b128 v[192:195], v151 offset:18432
	ds_read_b128 v[196:199], v151 offset:19456
	ds_read_b128 v[200:203], v151 offset:20480
	ds_read_b128 v[204:207], v151 offset:21504
	ds_read_b128 v[208:211], v151 offset:22528
	ds_read_b128 v[212:215], v151 offset:23552
	global_load_lds_dwordx4 v136, s[44:45]
	s_mov_b32 m0, vcc_lo
	s_addc_u32 s17, s45, 0
	global_load_lds_dwordx4 v140, s[44:45]
	s_mov_b32 m0, vcc_hi
	s_nop 0
	global_load_lds_dwordx4 v136, s[16:17]
	s_mov_b32 m0, s30
	s_nop 0
	global_load_lds_dwordx4 v140, s[16:17]
	s_mov_b32 m0, s22
	s_nop 0
	global_load_lds_dwordx4 v134, s[28:29]
	s_mov_b32 m0, s23
	s_nop 0
	global_load_lds_dwordx4 v138, s[28:29]
	s_waitcnt vmcnt(8)
	s_waitcnt lgkmcnt(0)
	s_barrier
	s_setprio 1
	s_waitcnt lgkmcnt(0)
	v_mfma_f32_16x16x32_bf16 v[52:55], v[146:149], v[184:187], v[52:55]
	v_mfma_f32_16x16x32_bf16 v[48:51], v[156:159], v[184:187], v[48:51]
	v_mfma_f32_16x16x32_bf16 v[32:35], v[156:159], v[192:195], v[32:35]
	v_mfma_f32_16x16x32_bf16 v[36:39], v[146:149], v[192:195], v[36:39]
	v_mfma_f32_16x16x32_bf16 v[20:23], v[146:149], v[200:203], v[20:23]
	v_mfma_f32_16x16x32_bf16 v[16:19], v[156:159], v[200:203], v[16:19]
	v_mfma_f32_16x16x32_bf16 v[0:3], v[156:159], v[208:211], v[0:3]
	v_mfma_f32_16x16x32_bf16 v[4:7], v[146:149], v[208:211], v[4:7]
	v_mfma_f32_16x16x32_bf16 v[52:55], v[152:155], v[188:191], v[52:55]
	v_mfma_f32_16x16x32_bf16 v[48:51], v[160:163], v[188:191], v[48:51]
	v_mfma_f32_16x16x32_bf16 v[32:35], v[160:163], v[196:199], v[32:35]
	v_mfma_f32_16x16x32_bf16 v[36:39], v[152:155], v[196:199], v[36:39]
	v_mfma_f32_16x16x32_bf16 v[20:23], v[152:155], v[204:207], v[20:23]
	v_mfma_f32_16x16x32_bf16 v[16:19], v[160:163], v[204:207], v[16:19]
	v_mfma_f32_16x16x32_bf16 v[0:3], v[160:163], v[212:215], v[0:3]
	v_mfma_f32_16x16x32_bf16 v[4:7], v[152:155], v[212:215], v[4:7]
	s_setprio 0
	s_setprio 1
	v_mfma_f32_16x16x32_bf16 v[60:63], v[164:167], v[184:187], v[60:63]
	v_mfma_f32_16x16x32_bf16 v[56:59], v[172:175], v[184:187], v[56:59]
	v_mfma_f32_16x16x32_bf16 v[40:43], v[172:175], v[192:195], v[40:43]
	v_mfma_f32_16x16x32_bf16 v[44:47], v[164:167], v[192:195], v[44:47]
	v_mfma_f32_16x16x32_bf16 v[28:31], v[164:167], v[200:203], v[28:31]
	v_mfma_f32_16x16x32_bf16 v[24:27], v[172:175], v[200:203], v[24:27]
	v_mfma_f32_16x16x32_bf16 v[8:11], v[172:175], v[208:211], v[8:11]
	v_mfma_f32_16x16x32_bf16 v[12:15], v[164:167], v[208:211], v[12:15]
	v_mfma_f32_16x16x32_bf16 v[60:63], v[168:171], v[188:191], v[60:63]
	v_mfma_f32_16x16x32_bf16 v[56:59], v[180:183], v[188:191], v[56:59]
	v_mfma_f32_16x16x32_bf16 v[40:43], v[180:183], v[196:199], v[40:43]
	v_mfma_f32_16x16x32_bf16 v[44:47], v[168:171], v[196:199], v[44:47]
	v_mfma_f32_16x16x32_bf16 v[28:31], v[168:171], v[204:207], v[28:31]
	v_mfma_f32_16x16x32_bf16 v[24:27], v[180:183], v[204:207], v[24:27]
	v_mfma_f32_16x16x32_bf16 v[8:11], v[180:183], v[212:215], v[8:11]
	v_mfma_f32_16x16x32_bf16 v[12:15], v[168:171], v[212:215], v[12:15]
	s_setprio 0
	s_barrier
; template <class Epi, class Sched, bool ALIGN_EPI = false, bool SP2 = false>
; __device__ __forceinline__ void gemm_phase(PG8_LAS unsigned char* lds, const Gemm g, const Sched& S, const Epi& E) {
;     ...
;         for (int t = (Epi::PEEL ? 2 : 0); t < nt; t += 2) {
;             const bool last = (t == nt - 2);
;             const char* a1 = cA + (size_t)(t + 1) * kstepA;
;             const char* a2 = last ? nA : cA + (size_t)(t + 2) * kstepA; const char* b2 = last ? nB : cB + (size_t)(t + 2) * kstepB;
;             const char* a3 = a2 + kstepA; const char* b3 = b2 + kstepB;
;             PG8_ITER(8);
	ds_read_b128 v[146:149], v132
	ds_read_b128 v[152:155], v132 offset:1024
	ds_read_b128 v[156:159], v132 offset:2048
	ds_read_b128 v[160:163], v132 offset:3072
	ds_read_b128 v[164:167], v133
	ds_read_b128 v[168:171], v133 offset:1024
	ds_read_b128 v[172:175], v133 offset:2048
	ds_read_b128 v[180:183], v133 offset:3072
	s_add_u32 s16, s28, 0x4000
	s_addc_u32 s17, s29, 0
	s_mov_b32 m0, s39
	ds_read_b128 v[184:187], v151 offset:32768
	ds_read_b128 v[188:191], v151 offset:33792
	ds_read_b128 v[192:195], v151 offset:34816
	ds_read_b128 v[196:199], v151 offset:35840
	ds_read_b128 v[200:203], v151 offset:36864
	ds_read_b128 v[204:207], v151 offset:37888
	ds_read_b128 v[208:211], v151 offset:38912
	ds_read_b128 v[212:215], v151 offset:39936
	global_load_lds_dwordx4 v134, s[16:17]
	s_mov_b32 m0, s56
	s_nop 0
	global_load_lds_dwordx4 v138, s[16:17]
	s_waitcnt vmcnt(8)
	s_waitcnt lgkmcnt(0)
	s_barrier
	s_setprio 1
	s_waitcnt lgkmcnt(0)
	v_mfma_f32_16x16x32_bf16 v[118:121], v[146:149], v[184:187], v[118:121]
	v_mfma_f32_16x16x32_bf16 v[114:117], v[156:159], v[184:187], v[114:117]
	v_mfma_f32_16x16x32_bf16 v[98:101], v[156:159], v[192:195], v[98:101]
	v_mfma_f32_16x16x32_bf16 v[102:105], v[146:149], v[192:195], v[102:105]
	v_mfma_f32_16x16x32_bf16 v[84:87], v[146:149], v[200:203], v[84:87]
	v_mfma_f32_16x16x32_bf16 v[80:83], v[156:159], v[200:203], v[80:83]
	v_mfma_f32_16x16x32_bf16 v[64:67], v[156:159], v[208:211], v[64:67]
	v_mfma_f32_16x16x32_bf16 v[68:71], v[146:149], v[208:211], v[68:71]
	v_mfma_f32_16x16x32_bf16 v[118:121], v[152:155], v[188:191], v[118:121]
	v_mfma_f32_16x16x32_bf16 v[114:117], v[160:163], v[188:191], v[114:117]
	v_mfma_f32_16x16x32_bf16 v[98:101], v[160:163], v[196:199], v[98:101]
	v_mfma_f32_16x16x32_bf16 v[102:105], v[152:155], v[196:199], v[102:105]
	v_mfma_f32_16x16x32_bf16 v[84:87], v[152:155], v[204:207], v[84:87]
	v_mfma_f32_16x16x32_bf16 v[80:83], v[160:163], v[204:207], v[80:83]
	v_mfma_f32_16x16x32_bf16 v[64:67], v[160:163], v[212:215], v[64:67]
	v_mfma_f32_16x16x32_bf16 v[68:71], v[152:155], v[212:215], v[68:71]
	s_setprio 0
	s_setprio 1
	v_mfma_f32_16x16x32_bf16 v[126:129], v[164:167], v[184:187], v[126:129]
	v_mfma_f32_16x16x32_bf16 v[122:125], v[172:175], v[184:187], v[122:125]
	v_mfma_f32_16x16x32_bf16 v[106:109], v[172:175], v[192:195], v[106:109]
	v_mfma_f32_16x16x32_bf16 v[110:113], v[164:167], v[192:195], v[110:113]
	v_mfma_f32_16x16x32_bf16 v[92:95], v[164:167], v[200:203], v[92:95]
	v_mfma_f32_16x16x32_bf16 v[88:91], v[172:175], v[200:203], v[88:91]
	v_mfma_f32_16x16x32_bf16 v[72:75], v[172:175], v[208:211], v[72:75]
	v_mfma_f32_16x16x32_bf16 v[76:79], v[164:167], v[208:211], v[76:79]
	v_mfma_f32_16x16x32_bf16 v[126:129], v[168:171], v[188:191], v[126:129]
	v_mfma_f32_16x16x32_bf16 v[122:125], v[180:183], v[188:191], v[122:125]
	v_mfma_f32_16x16x32_bf16 v[106:109], v[180:183], v[196:199], v[106:109]
	v_mfma_f32_16x16x32_bf16 v[110:113], v[168:171], v[196:199], v[110:113]
	v_mfma_f32_16x16x32_bf16 v[92:95], v[168:171], v[204:207], v[92:95]
	v_mfma_f32_16x16x32_bf16 v[88:91], v[180:183], v[204:207], v[88:91]
	v_mfma_f32_16x16x32_bf16 v[72:75], v[180:183], v[212:215], v[72:75]
	v_mfma_f32_16x16x32_bf16 v[76:79], v[168:171], v[212:215], v[76:79]
	s_setprio 0
	s_barrier
	s_mov_b32 m0, s31
	s_add_u32 s100, s44, 0x80
	s_addc_u32 s101, s45, 0
	s_add_u32 s16, s44, 0x40080
	ds_read_b128 v[184:187], v151 offset:49152
	ds_read_b128 v[188:191], v151 offset:50176
	ds_read_b128 v[192:195], v151 offset:51200
	ds_read_b128 v[196:199], v151 offset:52224
	ds_read_b128 v[200:203], v151 offset:53248
	ds_read_b128 v[204:207], v151 offset:54272
	ds_read_b128 v[208:211], v151 offset:55296
	ds_read_b128 v[212:215], v151 offset:56320
	global_load_lds_dwordx4 v136, s[100:101]
	s_mov_b32 m0, s12
	s_addc_u32 s17, s45, 0
	global_load_lds_dwordx4 v140, s[100:101]
	s_mov_b32 m0, s13
	s_nop 0
	global_load_lds_dwordx4 v136, s[16:17]
	s_mov_b32 m0, s11
	s_nop 0
	global_load_lds_dwordx4 v140, s[16:17]
	s_mov_b32 m0, s59
	s_nop 0
	global_load_lds_dwordx4 v134, s[42:43]
	s_mov_b32 m0, s96
	s_nop 0
	global_load_lds_dwordx4 v138, s[42:43]
	s_waitcnt vmcnt(8)
	s_waitcnt lgkmcnt(0)
	s_barrier
	s_setprio 1
	s_waitcnt lgkmcnt(0)
	v_mfma_f32_16x16x32_bf16 v[52:55], v[146:149], v[184:187], v[52:55]
	v_mfma_f32_16x16x32_bf16 v[48:51], v[156:159], v[184:187], v[48:51]
	v_mfma_f32_16x16x32_bf16 v[32:35], v[156:159], v[192:195], v[32:35]
	v_mfma_f32_16x16x32_bf16 v[36:39], v[146:149], v[192:195], v[36:39]
	v_mfma_f32_16x16x32_bf16 v[20:23], v[146:149], v[200:203], v[20:23]
	v_mfma_f32_16x16x32_bf16 v[16:19], v[156:159], v[200:203], v[16:19]
	v_mfma_f32_16x16x32_bf16 v[0:3], v[156:159], v[208:211], v[0:3]
	v_mfma_f32_16x16x32_bf16 v[4:7], v[146:149], v[208:211], v[4:7]
	v_mfma_f32_16x16x32_bf16 v[52:55], v[152:155], v[188:191], v[52:55]
	v_mfma_f32_16x16x32_bf16 v[48:51], v[160:163], v[188:191], v[48:51]
	v_mfma_f32_16x16x32_bf16 v[32:35], v[160:163], v[196:199], v[32:35]
	v_mfma_f32_16x16x32_bf16 v[36:39], v[152:155], v[196:199], v[36:39]
	v_mfma_f32_16x16x32_bf16 v[20:23], v[152:155], v[204:207], v[20:23]
	v_mfma_f32_16x16x32_bf16 v[16:19], v[160:163], v[204:207], v[16:19]
	v_mfma_f32_16x16x32_bf16 v[0:3], v[160:163], v[212:215], v[0:3]
	v_mfma_f32_16x16x32_bf16 v[4:7], v[152:155], v[212:215], v[4:7]
	s_setprio 0
	s_setprio 1
	v_mfma_f32_16x16x32_bf16 v[60:63], v[164:167], v[184:187], v[60:63]
	v_mfma_f32_16x16x32_bf16 v[56:59], v[172:175], v[184:187], v[56:59]
	v_mfma_f32_16x16x32_bf16 v[40:43], v[172:175], v[192:195], v[40:43]
	v_mfma_f32_16x16x32_bf16 v[44:47], v[164:167], v[192:195], v[44:47]
	v_mfma_f32_16x16x32_bf16 v[28:31], v[164:167], v[200:203], v[28:31]
	v_mfma_f32_16x16x32_bf16 v[24:27], v[172:175], v[200:203], v[24:27]
	v_mfma_f32_16x16x32_bf16 v[8:11], v[172:175], v[208:211], v[8:11]
	v_mfma_f32_16x16x32_bf16 v[12:15], v[164:167], v[208:211], v[12:15]
	v_mfma_f32_16x16x32_bf16 v[60:63], v[168:171], v[188:191], v[60:63]
	v_mfma_f32_16x16x32_bf16 v[56:59], v[180:183], v[188:191], v[56:59]
	v_mfma_f32_16x16x32_bf16 v[40:43], v[180:183], v[196:199], v[40:43]
	v_mfma_f32_16x16x32_bf16 v[44:47], v[168:171], v[196:199], v[44:47]
	v_mfma_f32_16x16x32_bf16 v[28:31], v[168:171], v[204:207], v[28:31]
	v_mfma_f32_16x16x32_bf16 v[24:27], v[180:183], v[204:207], v[24:27]
	v_mfma_f32_16x16x32_bf16 v[8:11], v[180:183], v[212:215], v[8:11]
	v_mfma_f32_16x16x32_bf16 v[12:15], v[168:171], v[212:215], v[12:15]
	s_setprio 0
	s_barrier
	s_add_i32 s18, s18, 2
	s_add_u32 s3, s3, 0x100
	s_addc_u32 s2, s2, 0
	s_add_u32 s24, s24, 0x800000
	s_addc_u32 s25, s25, 0
	s_cmp_gt_u32 s18, 13
	s_cbranch_scc0 .LBB0_250
	v_readlane_b32 s2, v255, 33
	v_readlane_b32 s3, v255, 34
	v_readlane_b32 s12, v255, 31
	s_and_b64 vcc, exec, s[2:3]
	v_readlane_b32 s13, v255, 32
	s_cbranch_vccz .LBB0_253
	s_barrier

.LBB0_345:
	s_add_i32 s10, s10, 2
	s_add_u32 s44, s42, s34
	s_addc_u32 s45, s43, s35
	s_add_i32 s18, 0, 0x10000
	s_and_b64 s[2:3], exec, s[46:47]
	s_cselect_b32 s3, s13, s59
	s_cselect_b32 s2, s12, s58
	s_add_i32 s38, 0, 0x14000
	v_add_u32_e32 v142, s18, v97
	v_add_u32_e32 v170, s38, v97
	ds_read_b128 v[122:125], v142
	ds_read_b128 v[126:129], v142 offset:1024
	ds_read_b128 v[138:141], v142 offset:2048
	ds_read_b128 v[142:145], v142 offset:3072
	ds_read_b128 v[146:149], v170
	ds_read_b128 v[150:153], v170 offset:1024
	ds_read_b128 v[154:157], v170 offset:2048
	ds_read_b128 v[170:173], v170 offset:3072
	s_add_i32 m0, s97, 0xc000
	ds_read_b128 v[174:177], v188
	ds_read_b128 v[180:183], v188 offset:1024
	ds_read_b128 v[184:187], v188 offset:2048
	ds_read_b128 v[190:193], v188 offset:3072
	ds_read_b128 v[194:197], v188 offset:4096
	ds_read_b128 v[198:201], v188 offset:5120
	ds_read_b128 v[202:205], v188 offset:6144
	ds_read_b128 v[206:209], v188 offset:7168
	global_load_lds_dwordx4 v168, s[24:25]
	s_add_i32 m0, s97, 0xe000
	s_nop 0
	global_load_lds_dwordx4 v166, s[24:25]
	s_waitcnt vmcnt(8)
	s_waitcnt lgkmcnt(0)
	s_barrier
	s_setprio 1
	s_waitcnt lgkmcnt(0)
	v_mfma_f32_16x16x32_bf16 v[134:137], v[122:125], v[174:177], v[134:137]
	v_mfma_f32_16x16x32_bf16 v[130:133], v[138:141], v[174:177], v[130:133]
	v_mfma_f32_16x16x32_bf16 v[106:109], v[138:141], v[184:187], v[106:109]
	v_mfma_f32_16x16x32_bf16 v[110:113], v[122:125], v[184:187], v[110:113]
	v_mfma_f32_16x16x32_bf16 v[92:95], v[122:125], v[194:197], v[92:95]
	v_mfma_f32_16x16x32_bf16 v[88:91], v[138:141], v[194:197], v[88:91]
	v_mfma_f32_16x16x32_bf16 v[72:75], v[138:141], v[202:205], v[72:75]
	v_mfma_f32_16x16x32_bf16 v[76:79], v[122:125], v[202:205], v[76:79]
	v_mfma_f32_16x16x32_bf16 v[134:137], v[126:129], v[180:183], v[134:137]
	v_mfma_f32_16x16x32_bf16 v[130:133], v[142:145], v[180:183], v[130:133]
	v_mfma_f32_16x16x32_bf16 v[106:109], v[142:145], v[190:193], v[106:109]
	v_mfma_f32_16x16x32_bf16 v[110:113], v[126:129], v[190:193], v[110:113]
	v_mfma_f32_16x16x32_bf16 v[92:95], v[126:129], v[198:201], v[92:95]
	v_mfma_f32_16x16x32_bf16 v[88:91], v[142:145], v[198:201], v[88:91]
	v_mfma_f32_16x16x32_bf16 v[72:75], v[142:145], v[206:209], v[72:75]
	v_mfma_f32_16x16x32_bf16 v[76:79], v[126:129], v[206:209], v[76:79]
	s_setprio 0
	s_setprio 1
	v_mfma_f32_16x16x32_bf16 v[118:121], v[146:149], v[174:177], v[118:121]
	v_mfma_f32_16x16x32_bf16 v[114:117], v[154:157], v[174:177], v[114:117]
	v_mfma_f32_16x16x32_bf16 v[98:101], v[154:157], v[184:187], v[98:101]
	v_mfma_f32_16x16x32_bf16 v[102:105], v[146:149], v[184:187], v[102:105]
	v_mfma_f32_16x16x32_bf16 v[84:87], v[146:149], v[194:197], v[84:87]
	v_mfma_f32_16x16x32_bf16 v[80:83], v[154:157], v[194:197], v[80:83]
	v_mfma_f32_16x16x32_bf16 v[64:67], v[154:157], v[202:205], v[64:67]
	v_mfma_f32_16x16x32_bf16 v[68:71], v[146:149], v[202:205], v[68:71]
	v_mfma_f32_16x16x32_bf16 v[118:121], v[150:153], v[180:183], v[118:121]
	v_mfma_f32_16x16x32_bf16 v[114:117], v[170:173], v[180:183], v[114:117]
	v_mfma_f32_16x16x32_bf16 v[98:101], v[170:173], v[190:193], v[98:101]
	v_mfma_f32_16x16x32_bf16 v[102:105], v[150:153], v[190:193], v[102:105]
	v_mfma_f32_16x16x32_bf16 v[84:87], v[150:153], v[198:201], v[84:87]
	v_mfma_f32_16x16x32_bf16 v[80:83], v[170:173], v[198:201], v[80:83]
	v_mfma_f32_16x16x32_bf16 v[64:67], v[170:173], v[206:209], v[64:67]
	v_mfma_f32_16x16x32_bf16 v[68:71], v[150:153], v[206:209], v[68:71]
	s_setprio 0
	s_barrier
	s_add_i32 s18, s18, s96
	v_lshl_add_u64 v[178:179], s[2:3], 0, v[162:163]
	s_mov_b32 m0, s18
	ds_read_b128 v[174:177], v188 offset:16384
	ds_read_b128 v[180:183], v188 offset:17408
	ds_read_b128 v[184:187], v188 offset:18432
	ds_read_b128 v[190:193], v188 offset:19456
	ds_read_b128 v[194:197], v188 offset:20480
	ds_read_b128 v[198:201], v188 offset:21504
	ds_read_b128 v[202:205], v188 offset:22528
	ds_read_b128 v[206:209], v188 offset:23552
	global_load_lds_dwordx4 v162, s[2:3]
	s_add_i32 m0, s18, 0x2000
	v_lshl_add_u64 v[210:211], s[2:3], 0, v[158:159]
	s_add_u32 s2, s2, s48
	s_addc_u32 s3, s3, 0
	s_add_i32 s18, s38, s96
	global_load_lds_dwordx4 v[210:211], off
	v_lshl_add_u64 v[212:213], s[2:3], 0, v[162:163]
	s_mov_b32 m0, s18
	v_lshl_add_u64 v[214:215], s[2:3], 0, v[158:159]
	global_load_lds_dwordx4 v162, s[2:3]
	s_add_i32 m0, s18, 0x2000
	s_nop 0
	global_load_lds_dwordx4 v158, s[2:3]
	s_mov_b32 m0, s97
	s_nop 0
	global_load_lds_dwordx4 v164, s[42:43]
	s_mov_b32 m0, s22
	s_nop 0
	global_load_lds_dwordx4 v160, s[42:43]
	s_waitcnt vmcnt(8)
	s_waitcnt lgkmcnt(0)
	s_barrier
	s_setprio 1
	s_waitcnt lgkmcnt(0)
	v_mfma_f32_16x16x32_bf16 v[60:63], v[122:125], v[174:177], v[60:63]
	v_mfma_f32_16x16x32_bf16 v[56:59], v[138:141], v[174:177], v[56:59]
	v_mfma_f32_16x16x32_bf16 v[40:43], v[138:141], v[184:187], v[40:43]
	v_mfma_f32_16x16x32_bf16 v[44:47], v[122:125], v[184:187], v[44:47]
	v_mfma_f32_16x16x32_bf16 v[28:31], v[122:125], v[194:197], v[28:31]
	v_mfma_f32_16x16x32_bf16 v[24:27], v[138:141], v[194:197], v[24:27]
	v_mfma_f32_16x16x32_bf16 v[8:11], v[138:141], v[202:205], v[8:11]
	v_mfma_f32_16x16x32_bf16 v[12:15], v[122:125], v[202:205], v[12:15]
	v_mfma_f32_16x16x32_bf16 v[60:63], v[126:129], v[180:183], v[60:63]
	v_mfma_f32_16x16x32_bf16 v[56:59], v[142:145], v[180:183], v[56:59]
	v_mfma_f32_16x16x32_bf16 v[40:43], v[142:145], v[190:193], v[40:43]
	v_mfma_f32_16x16x32_bf16 v[44:47], v[126:129], v[190:193], v[44:47]
	v_mfma_f32_16x16x32_bf16 v[28:31], v[126:129], v[198:201], v[28:31]
	v_mfma_f32_16x16x32_bf16 v[24:27], v[142:145], v[198:201], v[24:27]
	v_mfma_f32_16x16x32_bf16 v[8:11], v[142:145], v[206:209], v[8:11]
	v_mfma_f32_16x16x32_bf16 v[12:15], v[126:129], v[206:209], v[12:15]
	s_setprio 0
	s_setprio 1
	v_mfma_f32_16x16x32_bf16 v[52:55], v[146:149], v[174:177], v[52:55]
	v_mfma_f32_16x16x32_bf16 v[48:51], v[154:157], v[174:177], v[48:51]
	v_mfma_f32_16x16x32_bf16 v[32:35], v[154:157], v[184:187], v[32:35]
	v_mfma_f32_16x16x32_bf16 v[36:39], v[146:149], v[184:187], v[36:39]
	v_mfma_f32_16x16x32_bf16 v[20:23], v[146:149], v[194:197], v[20:23]
	v_mfma_f32_16x16x32_bf16 v[16:19], v[154:157], v[194:197], v[16:19]
	v_mfma_f32_16x16x32_bf16 v[0:3], v[154:157], v[202:205], v[0:3]
	v_mfma_f32_16x16x32_bf16 v[4:7], v[146:149], v[202:205], v[4:7]
	v_mfma_f32_16x16x32_bf16 v[52:55], v[150:153], v[180:183], v[52:55]
	v_mfma_f32_16x16x32_bf16 v[48:51], v[170:173], v[180:183], v[48:51]
	v_mfma_f32_16x16x32_bf16 v[32:35], v[170:173], v[190:193], v[32:35]
	v_mfma_f32_16x16x32_bf16 v[36:39], v[150:153], v[190:193], v[36:39]
	v_mfma_f32_16x16x32_bf16 v[20:23], v[150:153], v[198:201], v[20:23]
	v_mfma_f32_16x16x32_bf16 v[16:19], v[170:173], v[198:201], v[16:19]
	v_mfma_f32_16x16x32_bf16 v[0:3], v[170:173], v[206:209], v[0:3]
	v_mfma_f32_16x16x32_bf16 v[4:7], v[150:153], v[206:209], v[4:7]
	s_setprio 0
	s_barrier
	s_add_i32 s18, 0, 0x18000
	s_add_i32 s38, 0, 0x1c000
	v_add_u32_e32 v142, s18, v97
	v_add_u32_e32 v170, s38, v97
	ds_read_b128 v[122:125], v142
	ds_read_b128 v[126:129], v142 offset:1024
	ds_read_b128 v[138:141], v142 offset:2048
	ds_read_b128 v[142:145], v142 offset:3072
	ds_read_b128 v[146:149], v170
	ds_read_b128 v[150:153], v170 offset:1024
	ds_read_b128 v[154:157], v170 offset:2048
	ds_read_b128 v[170:173], v170 offset:3072
	s_add_u32 s2, s42, s98
	s_addc_u32 s3, s43, 0
	s_mov_b32 m0, s23
	ds_read_b128 v[174:177], v188 offset:32768
	ds_read_b128 v[180:183], v188 offset:33792
	ds_read_b128 v[184:187], v188 offset:34816
	ds_read_b128 v[190:193], v188 offset:35840
	ds_read_b128 v[194:197], v188 offset:36864
	ds_read_b128 v[198:201], v188 offset:37888
	ds_read_b128 v[202:205], v188 offset:38912
	ds_read_b128 v[206:209], v188 offset:39936
	global_load_lds_dwordx4 v164, s[2:3]
	s_mov_b32 m0, s19
	s_nop 0
	global_load_lds_dwordx4 v160, s[2:3]
	s_waitcnt vmcnt(8)
	s_waitcnt lgkmcnt(0)
	s_barrier
	s_setprio 1
	s_waitcnt lgkmcnt(0)
	v_mfma_f32_16x16x32_bf16 v[134:137], v[122:125], v[174:177], v[134:137]
	v_mfma_f32_16x16x32_bf16 v[130:133], v[138:141], v[174:177], v[130:133]
	v_mfma_f32_16x16x32_bf16 v[106:109], v[138:141], v[184:187], v[106:109]
	v_mfma_f32_16x16x32_bf16 v[110:113], v[122:125], v[184:187], v[110:113]
	v_mfma_f32_16x16x32_bf16 v[92:95], v[122:125], v[194:197], v[92:95]
	v_mfma_f32_16x16x32_bf16 v[88:91], v[138:141], v[194:197], v[88:91]
	v_mfma_f32_16x16x32_bf16 v[72:75], v[138:141], v[202:205], v[72:75]
	v_mfma_f32_16x16x32_bf16 v[76:79], v[122:125], v[202:205], v[76:79]
	v_mfma_f32_16x16x32_bf16 v[134:137], v[126:129], v[180:183], v[134:137]
	v_mfma_f32_16x16x32_bf16 v[130:133], v[142:145], v[180:183], v[130:133]
	v_mfma_f32_16x16x32_bf16 v[106:109], v[142:145], v[190:193], v[106:109]
	v_mfma_f32_16x16x32_bf16 v[110:113], v[126:129], v[190:193], v[110:113]
	v_mfma_f32_16x16x32_bf16 v[92:95], v[126:129], v[198:201], v[92:95]
	v_mfma_f32_16x16x32_bf16 v[88:91], v[142:145], v[198:201], v[88:91]
	v_mfma_f32_16x16x32_bf16 v[72:75], v[142:145], v[206:209], v[72:75]
	v_mfma_f32_16x16x32_bf16 v[76:79], v[126:129], v[206:209], v[76:79]
	s_setprio 0
	s_setprio 1
	v_mfma_f32_16x16x32_bf16 v[118:121], v[146:149], v[174:177], v[118:121]
	v_mfma_f32_16x16x32_bf16 v[114:117], v[154:157], v[174:177], v[114:117]
	v_mfma_f32_16x16x32_bf16 v[98:101], v[154:157], v[184:187], v[98:101]
	v_mfma_f32_16x16x32_bf16 v[102:105], v[146:149], v[184:187], v[102:105]
	v_mfma_f32_16x16x32_bf16 v[84:87], v[146:149], v[194:197], v[84:87]
	v_mfma_f32_16x16x32_bf16 v[80:83], v[154:157], v[194:197], v[80:83]
	v_mfma_f32_16x16x32_bf16 v[64:67], v[154:157], v[202:205], v[64:67]
	v_mfma_f32_16x16x32_bf16 v[68:71], v[146:149], v[202:205], v[68:71]
	v_mfma_f32_16x16x32_bf16 v[118:121], v[150:153], v[180:183], v[118:121]
	v_mfma_f32_16x16x32_bf16 v[114:117], v[170:173], v[180:183], v[114:117]
	v_mfma_f32_16x16x32_bf16 v[98:101], v[170:173], v[190:193], v[98:101]
	v_mfma_f32_16x16x32_bf16 v[102:105], v[150:153], v[190:193], v[102:105]
	v_mfma_f32_16x16x32_bf16 v[84:87], v[150:153], v[198:201], v[84:87]
	v_mfma_f32_16x16x32_bf16 v[80:83], v[170:173], v[198:201], v[80:83]
	v_mfma_f32_16x16x32_bf16 v[64:67], v[170:173], v[206:209], v[64:67]
	v_mfma_f32_16x16x32_bf16 v[68:71], v[150:153], v[206:209], v[68:71]
	s_setprio 0
	s_barrier
; template <class Epi, class Sched, bool ALIGN_EPI = false, bool SP2 = false>
; __device__ __forceinline__ void gemm_phase(PG8_LAS unsigned char* lds, const Gemm g, const Sched& S, const Epi& E) {
;     ...
;         for (int t = (Epi::PEEL ? 2 : 0); t < nt; t += 2) {
;             const bool last = (t == nt - 2);
;             const char* a1 = cA + (size_t)(t + 1) * kstepA;
;             const char* a2 = last ? nA : cA + (size_t)(t + 2) * kstepA; const char* b2 = last ? nB : cB + (size_t)(t + 2) * kstepB;
;             const char* a3 = a2 + kstepA; const char* b3 = b2 + kstepB;
;             PG8_ITER(8);
	s_add_i32 s2, s18, s96
	v_lshl_add_u64 v[178:179], v[178:179], 0, s[36:37]
	s_mov_b32 m0, s2
	ds_read_b128 v[174:177], v188 offset:49152
	ds_read_b128 v[180:183], v188 offset:50176
	ds_read_b128 v[184:187], v188 offset:51200
	ds_read_b128 v[190:193], v188 offset:52224
	ds_read_b128 v[194:197], v188 offset:53248
	ds_read_b128 v[198:201], v188 offset:54272
	ds_read_b128 v[202:205], v188 offset:55296
	ds_read_b128 v[206:209], v188 offset:56320
	global_load_lds_dwordx4 v[178:179], off
	v_lshl_add_u64 v[178:179], v[210:211], 0, s[36:37]
	s_add_i32 m0, s2, 0x2000
	s_add_i32 s2, s38, s96
	global_load_lds_dwordx4 v[178:179], off
	v_lshl_add_u64 v[178:179], v[212:213], 0, s[36:37]
	s_mov_b32 m0, s2
	s_nop 0
	global_load_lds_dwordx4 v[178:179], off
	v_lshl_add_u64 v[178:179], v[214:215], 0, s[36:37]
	s_add_i32 m0, s2, 0x2000
	s_nop 0
	global_load_lds_dwordx4 v[178:179], off
	s_mov_b32 m0, s6
	s_nop 0
	global_load_lds_dwordx4 v164, s[44:45]
	s_mov_b32 m0, s56
	s_nop 0
	global_load_lds_dwordx4 v160, s[44:45]
	s_waitcnt vmcnt(8)
	s_waitcnt lgkmcnt(0)
	s_barrier
	s_setprio 1
	s_waitcnt lgkmcnt(0)
	v_mfma_f32_16x16x32_bf16 v[60:63], v[122:125], v[174:177], v[60:63]
	v_mfma_f32_16x16x32_bf16 v[56:59], v[138:141], v[174:177], v[56:59]
	v_mfma_f32_16x16x32_bf16 v[40:43], v[138:141], v[184:187], v[40:43]
	v_mfma_f32_16x16x32_bf16 v[44:47], v[122:125], v[184:187], v[44:47]
	v_mfma_f32_16x16x32_bf16 v[28:31], v[122:125], v[194:197], v[28:31]
	v_mfma_f32_16x16x32_bf16 v[24:27], v[138:141], v[194:197], v[24:27]
	v_mfma_f32_16x16x32_bf16 v[8:11], v[138:141], v[202:205], v[8:11]
	v_mfma_f32_16x16x32_bf16 v[12:15], v[122:125], v[202:205], v[12:15]
	v_mfma_f32_16x16x32_bf16 v[60:63], v[126:129], v[180:183], v[60:63]
	v_mfma_f32_16x16x32_bf16 v[56:59], v[142:145], v[180:183], v[56:59]
	v_mfma_f32_16x16x32_bf16 v[40:43], v[142:145], v[190:193], v[40:43]
	v_mfma_f32_16x16x32_bf16 v[44:47], v[126:129], v[190:193], v[44:47]
	v_mfma_f32_16x16x32_bf16 v[28:31], v[126:129], v[198:201], v[28:31]
	v_mfma_f32_16x16x32_bf16 v[24:27], v[142:145], v[198:201], v[24:27]
	v_mfma_f32_16x16x32_bf16 v[8:11], v[142:145], v[206:209], v[8:11]
	v_mfma_f32_16x16x32_bf16 v[12:15], v[126:129], v[206:209], v[12:15]
	s_setprio 0
	s_setprio 1
	v_mfma_f32_16x16x32_bf16 v[52:55], v[146:149], v[174:177], v[52:55]
	v_mfma_f32_16x16x32_bf16 v[48:51], v[154:157], v[174:177], v[48:51]
	v_mfma_f32_16x16x32_bf16 v[32:35], v[154:157], v[184:187], v[32:35]
	v_mfma_f32_16x16x32_bf16 v[36:39], v[146:149], v[184:187], v[36:39]
	v_mfma_f32_16x16x32_bf16 v[20:23], v[146:149], v[194:197], v[20:23]
	v_mfma_f32_16x16x32_bf16 v[16:19], v[154:157], v[194:197], v[16:19]
	v_mfma_f32_16x16x32_bf16 v[0:3], v[154:157], v[202:205], v[0:3]
	v_mfma_f32_16x16x32_bf16 v[4:7], v[146:149], v[202:205], v[4:7]
	v_mfma_f32_16x16x32_bf16 v[52:55], v[150:153], v[180:183], v[52:55]
	v_mfma_f32_16x16x32_bf16 v[48:51], v[170:173], v[180:183], v[48:51]
	v_mfma_f32_16x16x32_bf16 v[32:35], v[170:173], v[190:193], v[32:35]
	v_mfma_f32_16x16x32_bf16 v[36:39], v[150:153], v[190:193], v[36:39]
	v_mfma_f32_16x16x32_bf16 v[20:23], v[150:153], v[198:201], v[20:23]
	v_mfma_f32_16x16x32_bf16 v[16:19], v[170:173], v[198:201], v[16:19]
	v_mfma_f32_16x16x32_bf16 v[0:3], v[170:173], v[206:209], v[0:3]
	v_mfma_f32_16x16x32_bf16 v[4:7], v[150:153], v[206:209], v[4:7]
	s_setprio 0
	s_barrier
	s_add_u32 s58, s58, 0x100
	s_addc_u32 s59, s59, 0
	s_add_u32 s24, s24, s49
	s_addc_u32 s25, s25, 0
	s_cmp_ge_u32 s10, s8
	s_cbranch_scc1 .LBB0_348

; template <class Epi, class Sched, bool ALIGN_EPI = false, bool SP2 = false>
; __device__ __forceinline__ void gemm_phase(PG8_LAS unsigned char* lds, const Gemm g, const Sched& S, const Epi& E) {
;     ...
;             const char* a1 = cA + kstepA; const char* a2 = cA + 2 * kstepA; const char* b2 = cB + 2 * kstepB; const char* a3 = a2 + kstepA; const char* b3 = b2 + kstepB;
;             PG8_ITER(8);
;         }
;         for (int t = (Epi::PEEL ? 2 : 0); t < nt; t += 2) {
;             const bool last = (t == nt - 2);
;             const char* a1 = cA + (size_t)(t + 1) * kstepA;
;             const char* a2 = last ? nA : cA + (size_t)(t + 2) * kstepA; const char* b2 = last ? nB : cB + (size_t)(t + 2) * kstepB;
;             const char* a3 = a2 + kstepA; const char* b3 = b2 + kstepB;
.LBB0_478:
	ds_read_b128 v[146:149], v142
	ds_read_b128 v[150:153], v142 offset:1024
	ds_read_b128 v[158:161], v142 offset:2048
	ds_read_b128 v[162:165], v142 offset:3072
	ds_read_b128 v[166:169], v143
	ds_read_b128 v[170:173], v143 offset:1024
	ds_read_b128 v[174:177], v143 offset:2048
	ds_read_b128 v[180:183], v143 offset:3072
	s_add_u32 s10, s0, 0x3fc000
	s_addc_u32 s11, s1, 0
	s_cmp_eq_u32 s18, 12
	s_cselect_b32 s44, s27, s10
	s_cselect_b32 s45, s25, s11
	s_cselect_b32 s42, s58, s3
	s_cselect_b32 s43, s57, s2
	s_add_u32 s34, s44, 0x400000
	s_addc_u32 s35, s45, 0
	s_mov_b32 m0, s59
	ds_read_b128 v[184:187], v156
	ds_read_b128 v[188:191], v156 offset:1024
	ds_read_b128 v[192:195], v156 offset:2048
	ds_read_b128 v[196:199], v156 offset:3072
	ds_read_b128 v[200:203], v156 offset:4096
	ds_read_b128 v[204:207], v156 offset:5120
	ds_read_b128 v[208:211], v156 offset:6144
	ds_read_b128 v[212:215], v156 offset:7168
	global_load_lds_dwordx4 v140, s[0:1]
	s_mov_b32 m0, s60
	s_nop 0
	global_load_lds_dwordx4 v138, s[0:1]
	s_waitcnt vmcnt(8)
	s_waitcnt lgkmcnt(0)
	s_barrier
	s_setprio 1
	s_waitcnt lgkmcnt(0)
	v_mfma_f32_16x16x32_bf16 v[122:125], v[146:149], v[184:187], v[122:125]
	v_mfma_f32_16x16x32_bf16 v[114:117], v[158:161], v[184:187], v[114:117]
	v_mfma_f32_16x16x32_bf16 v[98:101], v[158:161], v[192:195], v[98:101]
	v_mfma_f32_16x16x32_bf16 v[106:109], v[146:149], v[192:195], v[106:109]
	v_mfma_f32_16x16x32_bf16 v[88:91], v[146:149], v[200:203], v[88:91]
	v_mfma_f32_16x16x32_bf16 v[80:83], v[158:161], v[200:203], v[80:83]
	v_mfma_f32_16x16x32_bf16 v[60:63], v[158:161], v[208:211], v[60:63]
	v_mfma_f32_16x16x32_bf16 v[72:75], v[146:149], v[208:211], v[72:75]
	v_mfma_f32_16x16x32_bf16 v[122:125], v[150:153], v[188:191], v[122:125]
	v_mfma_f32_16x16x32_bf16 v[114:117], v[162:165], v[188:191], v[114:117]
	v_mfma_f32_16x16x32_bf16 v[98:101], v[162:165], v[196:199], v[98:101]
	v_mfma_f32_16x16x32_bf16 v[106:109], v[150:153], v[196:199], v[106:109]
	v_mfma_f32_16x16x32_bf16 v[88:91], v[150:153], v[204:207], v[88:91]
	v_mfma_f32_16x16x32_bf16 v[80:83], v[162:165], v[204:207], v[80:83]
	v_mfma_f32_16x16x32_bf16 v[60:63], v[162:165], v[212:215], v[60:63]
	v_mfma_f32_16x16x32_bf16 v[72:75], v[150:153], v[212:215], v[72:75]
	s_setprio 0
	s_setprio 1
	v_mfma_f32_16x16x32_bf16 v[126:129], v[166:169], v[184:187], v[126:129]
	v_mfma_f32_16x16x32_bf16 v[118:121], v[174:177], v[184:187], v[118:121]
	v_mfma_f32_16x16x32_bf16 v[102:105], v[174:177], v[192:195], v[102:105]
	v_mfma_f32_16x16x32_bf16 v[110:113], v[166:169], v[192:195], v[110:113]
	v_mfma_f32_16x16x32_bf16 v[92:95], v[166:169], v[200:203], v[92:95]
	v_mfma_f32_16x16x32_bf16 v[84:87], v[174:177], v[200:203], v[84:87]
	v_mfma_f32_16x16x32_bf16 v[68:71], v[174:177], v[208:211], v[68:71]
	v_mfma_f32_16x16x32_bf16 v[76:79], v[166:169], v[208:211], v[76:79]
	v_mfma_f32_16x16x32_bf16 v[126:129], v[170:173], v[188:191], v[126:129]
	v_mfma_f32_16x16x32_bf16 v[118:121], v[180:183], v[188:191], v[118:121]
	v_mfma_f32_16x16x32_bf16 v[102:105], v[180:183], v[196:199], v[102:105]
	v_mfma_f32_16x16x32_bf16 v[110:113], v[170:173], v[196:199], v[110:113]
	v_mfma_f32_16x16x32_bf16 v[92:95], v[170:173], v[204:207], v[92:95]
	v_mfma_f32_16x16x32_bf16 v[84:87], v[180:183], v[204:207], v[84:87]
	v_mfma_f32_16x16x32_bf16 v[68:71], v[180:183], v[212:215], v[68:71]
	v_mfma_f32_16x16x32_bf16 v[76:79], v[170:173], v[212:215], v[76:79]
	s_setprio 0
	s_barrier
	s_mov_b32 m0, s61
	s_add_u32 s10, s42, 0x40000
	ds_read_b128 v[184:187], v156 offset:16384
	ds_read_b128 v[188:191], v156 offset:17408
	ds_read_b128 v[192:195], v156 offset:18432
	ds_read_b128 v[196:199], v156 offset:19456
	ds_read_b128 v[200:203], v156 offset:20480
	ds_read_b128 v[204:207], v156 offset:21504
	ds_read_b128 v[208:211], v156 offset:22528
	ds_read_b128 v[212:215], v156 offset:23552
	global_load_lds_dwordx4 v132, s[42:43]
	s_mov_b32 m0, s96
	s_addc_u32 s11, s43, 0
	global_load_lds_dwordx4 v136, s[42:43]
	s_mov_b32 m0, s97
	s_nop 0
	global_load_lds_dwordx4 v132, s[10:11]
	s_mov_b32 m0, s98
	s_nop 0
	global_load_lds_dwordx4 v136, s[10:11]
	s_mov_b32 m0, s23
	s_nop 0
	global_load_lds_dwordx4 v130, s[44:45]
	s_mov_b32 m0, s39
	s_nop 0
	global_load_lds_dwordx4 v134, s[44:45]
	s_waitcnt vmcnt(8)
	s_waitcnt lgkmcnt(0)
	s_barrier
	s_setprio 1
	s_waitcnt lgkmcnt(0)
	v_mfma_f32_16x16x32_bf16 v[56:59], v[146:149], v[184:187], v[56:59]
	v_mfma_f32_16x16x32_bf16 v[48:51], v[158:161], v[184:187], v[48:51]
	v_mfma_f32_16x16x32_bf16 v[32:35], v[158:161], v[192:195], v[32:35]
	v_mfma_f32_16x16x32_bf16 v[40:43], v[146:149], v[192:195], v[40:43]
	v_mfma_f32_16x16x32_bf16 v[24:27], v[146:149], v[200:203], v[24:27]
	v_mfma_f32_16x16x32_bf16 v[16:19], v[158:161], v[200:203], v[16:19]
	v_mfma_f32_16x16x32_bf16 v[0:3], v[158:161], v[208:211], v[0:3]
	v_mfma_f32_16x16x32_bf16 v[8:11], v[146:149], v[208:211], v[8:11]
	v_mfma_f32_16x16x32_bf16 v[56:59], v[150:153], v[188:191], v[56:59]
	v_mfma_f32_16x16x32_bf16 v[48:51], v[162:165], v[188:191], v[48:51]
	v_mfma_f32_16x16x32_bf16 v[32:35], v[162:165], v[196:199], v[32:35]
	v_mfma_f32_16x16x32_bf16 v[40:43], v[150:153], v[196:199], v[40:43]
	v_mfma_f32_16x16x32_bf16 v[24:27], v[150:153], v[204:207], v[24:27]
	v_mfma_f32_16x16x32_bf16 v[16:19], v[162:165], v[204:207], v[16:19]
	v_mfma_f32_16x16x32_bf16 v[0:3], v[162:165], v[212:215], v[0:3]
	v_mfma_f32_16x16x32_bf16 v[8:11], v[150:153], v[212:215], v[8:11]
	s_setprio 0
	s_setprio 1
	v_mfma_f32_16x16x32_bf16 v[64:67], v[166:169], v[184:187], v[64:67]
	v_mfma_f32_16x16x32_bf16 v[52:55], v[174:177], v[184:187], v[52:55]
	v_mfma_f32_16x16x32_bf16 v[36:39], v[174:177], v[192:195], v[36:39]
	v_mfma_f32_16x16x32_bf16 v[44:47], v[166:169], v[192:195], v[44:47]
	v_mfma_f32_16x16x32_bf16 v[28:31], v[166:169], v[200:203], v[28:31]
	v_mfma_f32_16x16x32_bf16 v[20:23], v[174:177], v[200:203], v[20:23]
	v_mfma_f32_16x16x32_bf16 v[4:7], v[174:177], v[208:211], v[4:7]
	v_mfma_f32_16x16x32_bf16 v[12:15], v[166:169], v[208:211], v[12:15]
	v_mfma_f32_16x16x32_bf16 v[64:67], v[170:173], v[188:191], v[64:67]
	v_mfma_f32_16x16x32_bf16 v[52:55], v[180:183], v[188:191], v[52:55]
	v_mfma_f32_16x16x32_bf16 v[36:39], v[180:183], v[196:199], v[36:39]
	v_mfma_f32_16x16x32_bf16 v[44:47], v[170:173], v[196:199], v[44:47]
	v_mfma_f32_16x16x32_bf16 v[28:31], v[170:173], v[204:207], v[28:31]
	v_mfma_f32_16x16x32_bf16 v[20:23], v[180:183], v[204:207], v[20:23]
	v_mfma_f32_16x16x32_bf16 v[4:7], v[180:183], v[212:215], v[4:7]
	v_mfma_f32_16x16x32_bf16 v[12:15], v[170:173], v[212:215], v[12:15]
	s_setprio 0
	s_barrier
; #define PG8_BAR __builtin_amdgcn_s_barrier()
; template <class Epi, class Sched, bool ALIGN_EPI = false, bool SP2 = false>
; __device__ __forceinline__ void gemm_phase(PG8_LAS unsigned char* lds, const Gemm g, const Sched& S, const Epi& E) {
;     ...
;         if constexpr (Epi::PEEL) {
;             const char* a1 = cA + kstepA; const char* a2 = cA + 2 * kstepA; const char* b2 = cB + 2 * kstepB; const char* a3 = a2 + kstepA; const char* b3 = b2 + kstepB;
;             PG8_ITER(8);
;         }
;         for (int t = (Epi::PEEL ? 2 : 0); t < nt; t += 2) {
;             const bool last = (t == nt - 2);
;             const char* a1 = cA + (size_t)(t + 1) * kstepA;
;             const char* a2 = last ? nA : cA + (size_t)(t + 2) * kstepA; const char* b2 = last ? nB : cB + (size_t)(t + 2) * kstepB;
;             const char* a3 = a2 + kstepA; const char* b3 = b2 + kstepB;
;             PG8_ITER(8);
;         }
;     ...
;         if constexpr (ALIGN_EPI) { if (wr == 0) PG8_BAR; }
	ds_read_b128 v[146:149], v144
	ds_read_b128 v[150:153], v144 offset:1024
	ds_read_b128 v[158:161], v144 offset:2048
	ds_read_b128 v[162:165], v144 offset:3072
	ds_read_b128 v[166:169], v145
	ds_read_b128 v[170:173], v145 offset:1024
	ds_read_b128 v[174:177], v145 offset:2048
	ds_read_b128 v[180:183], v145 offset:3072
	s_add_u32 s10, s44, 0x4000
	s_addc_u32 s11, s45, 0
	s_mov_b32 m0, s46
	ds_read_b128 v[184:187], v156 offset:32768
	ds_read_b128 v[188:191], v156 offset:33792
	ds_read_b128 v[192:195], v156 offset:34816
	ds_read_b128 v[196:199], v156 offset:35840
	ds_read_b128 v[200:203], v156 offset:36864
	ds_read_b128 v[204:207], v156 offset:37888
	ds_read_b128 v[208:211], v156 offset:38912
	ds_read_b128 v[212:215], v156 offset:39936
	global_load_lds_dwordx4 v130, s[10:11]
	s_mov_b32 m0, s47
	s_nop 0
	global_load_lds_dwordx4 v134, s[10:11]
	s_waitcnt vmcnt(8)
	s_waitcnt lgkmcnt(0)
	s_barrier
	s_setprio 1
	s_waitcnt lgkmcnt(0)
	v_mfma_f32_16x16x32_bf16 v[122:125], v[146:149], v[184:187], v[122:125]
	v_mfma_f32_16x16x32_bf16 v[114:117], v[158:161], v[184:187], v[114:117]
	v_mfma_f32_16x16x32_bf16 v[98:101], v[158:161], v[192:195], v[98:101]
	v_mfma_f32_16x16x32_bf16 v[106:109], v[146:149], v[192:195], v[106:109]
	v_mfma_f32_16x16x32_bf16 v[88:91], v[146:149], v[200:203], v[88:91]
	v_mfma_f32_16x16x32_bf16 v[80:83], v[158:161], v[200:203], v[80:83]
	v_mfma_f32_16x16x32_bf16 v[60:63], v[158:161], v[208:211], v[60:63]
	v_mfma_f32_16x16x32_bf16 v[72:75], v[146:149], v[208:211], v[72:75]
	v_mfma_f32_16x16x32_bf16 v[122:125], v[150:153], v[188:191], v[122:125]
	v_mfma_f32_16x16x32_bf16 v[114:117], v[162:165], v[188:191], v[114:117]
	v_mfma_f32_16x16x32_bf16 v[98:101], v[162:165], v[196:199], v[98:101]
	v_mfma_f32_16x16x32_bf16 v[106:109], v[150:153], v[196:199], v[106:109]
	v_mfma_f32_16x16x32_bf16 v[88:91], v[150:153], v[204:207], v[88:91]
	v_mfma_f32_16x16x32_bf16 v[80:83], v[162:165], v[204:207], v[80:83]
	v_mfma_f32_16x16x32_bf16 v[60:63], v[162:165], v[212:215], v[60:63]
	v_mfma_f32_16x16x32_bf16 v[72:75], v[150:153], v[212:215], v[72:75]
	s_setprio 0
	s_setprio 1
	v_mfma_f32_16x16x32_bf16 v[126:129], v[166:169], v[184:187], v[126:129]
	v_mfma_f32_16x16x32_bf16 v[118:121], v[174:177], v[184:187], v[118:121]
	v_mfma_f32_16x16x32_bf16 v[102:105], v[174:177], v[192:195], v[102:105]
	v_mfma_f32_16x16x32_bf16 v[110:113], v[166:169], v[192:195], v[110:113]
	v_mfma_f32_16x16x32_bf16 v[92:95], v[166:169], v[200:203], v[92:95]
	v_mfma_f32_16x16x32_bf16 v[84:87], v[174:177], v[200:203], v[84:87]
	v_mfma_f32_16x16x32_bf16 v[68:71], v[174:177], v[208:211], v[68:71]
	v_mfma_f32_16x16x32_bf16 v[76:79], v[166:169], v[208:211], v[76:79]
	v_mfma_f32_16x16x32_bf16 v[126:129], v[170:173], v[188:191], v[126:129]
	v_mfma_f32_16x16x32_bf16 v[118:121], v[180:183], v[188:191], v[118:121]
	v_mfma_f32_16x16x32_bf16 v[102:105], v[180:183], v[196:199], v[102:105]
	v_mfma_f32_16x16x32_bf16 v[110:113], v[170:173], v[196:199], v[110:113]
	v_mfma_f32_16x16x32_bf16 v[92:95], v[170:173], v[204:207], v[92:95]
	v_mfma_f32_16x16x32_bf16 v[84:87], v[180:183], v[204:207], v[84:87]
	v_mfma_f32_16x16x32_bf16 v[68:71], v[180:183], v[212:215], v[68:71]
	v_mfma_f32_16x16x32_bf16 v[76:79], v[170:173], v[212:215], v[76:79]
	s_setprio 0
	s_barrier
	s_mov_b32 m0, s99
	s_add_u32 s100, s42, 0x80
	s_addc_u32 s101, s43, 0
	s_add_u32 s10, s42, 0x40080
	ds_read_b128 v[184:187], v156 offset:49152
	ds_read_b128 v[188:191], v156 offset:50176
	ds_read_b128 v[192:195], v156 offset:51200
	ds_read_b128 v[196:199], v156 offset:52224
	ds_read_b128 v[200:203], v156 offset:53248
	ds_read_b128 v[204:207], v156 offset:54272
	ds_read_b128 v[208:211], v156 offset:55296
	ds_read_b128 v[212:215], v156 offset:56320
	global_load_lds_dwordx4 v132, s[100:101]
	s_mov_b32 m0, vcc_lo
	s_addc_u32 s11, s43, 0
	global_load_lds_dwordx4 v136, s[100:101]
	s_mov_b32 m0, vcc_hi
	s_nop 0
	global_load_lds_dwordx4 v132, s[10:11]
	s_mov_b32 m0, s38
	s_nop 0
	global_load_lds_dwordx4 v136, s[10:11]
	s_mov_b32 m0, s49
	s_nop 0
	global_load_lds_dwordx4 v130, s[34:35]
	s_mov_b32 m0, s50
	s_nop 0
	global_load_lds_dwordx4 v134, s[34:35]
	s_waitcnt vmcnt(8)
	s_waitcnt lgkmcnt(0)
	s_barrier
	s_setprio 1
	s_waitcnt lgkmcnt(0)
	v_mfma_f32_16x16x32_bf16 v[56:59], v[146:149], v[184:187], v[56:59]
	v_mfma_f32_16x16x32_bf16 v[48:51], v[158:161], v[184:187], v[48:51]
	v_mfma_f32_16x16x32_bf16 v[32:35], v[158:161], v[192:195], v[32:35]
	v_mfma_f32_16x16x32_bf16 v[40:43], v[146:149], v[192:195], v[40:43]
	v_mfma_f32_16x16x32_bf16 v[24:27], v[146:149], v[200:203], v[24:27]
	v_mfma_f32_16x16x32_bf16 v[16:19], v[158:161], v[200:203], v[16:19]
	v_mfma_f32_16x16x32_bf16 v[0:3], v[158:161], v[208:211], v[0:3]
	v_mfma_f32_16x16x32_bf16 v[8:11], v[146:149], v[208:211], v[8:11]
	v_mfma_f32_16x16x32_bf16 v[56:59], v[150:153], v[188:191], v[56:59]
	v_mfma_f32_16x16x32_bf16 v[48:51], v[162:165], v[188:191], v[48:51]
	v_mfma_f32_16x16x32_bf16 v[32:35], v[162:165], v[196:199], v[32:35]
	v_mfma_f32_16x16x32_bf16 v[40:43], v[150:153], v[196:199], v[40:43]
	v_mfma_f32_16x16x32_bf16 v[24:27], v[150:153], v[204:207], v[24:27]
	v_mfma_f32_16x16x32_bf16 v[16:19], v[162:165], v[204:207], v[16:19]
	v_mfma_f32_16x16x32_bf16 v[0:3], v[162:165], v[212:215], v[0:3]
	v_mfma_f32_16x16x32_bf16 v[8:11], v[150:153], v[212:215], v[8:11]
	s_setprio 0
	s_setprio 1
	v_mfma_f32_16x16x32_bf16 v[64:67], v[166:169], v[184:187], v[64:67]
	v_mfma_f32_16x16x32_bf16 v[52:55], v[174:177], v[184:187], v[52:55]
	v_mfma_f32_16x16x32_bf16 v[36:39], v[174:177], v[192:195], v[36:39]
	v_mfma_f32_16x16x32_bf16 v[44:47], v[166:169], v[192:195], v[44:47]
	v_mfma_f32_16x16x32_bf16 v[28:31], v[166:169], v[200:203], v[28:31]
	v_mfma_f32_16x16x32_bf16 v[20:23], v[174:177], v[200:203], v[20:23]
	v_mfma_f32_16x16x32_bf16 v[4:7], v[174:177], v[208:211], v[4:7]
	v_mfma_f32_16x16x32_bf16 v[12:15], v[166:169], v[208:211], v[12:15]
	v_mfma_f32_16x16x32_bf16 v[64:67], v[170:173], v[188:191], v[64:67]
	v_mfma_f32_16x16x32_bf16 v[52:55], v[180:183], v[188:191], v[52:55]
	v_mfma_f32_16x16x32_bf16 v[36:39], v[180:183], v[196:199], v[36:39]
	v_mfma_f32_16x16x32_bf16 v[44:47], v[170:173], v[196:199], v[44:47]
	v_mfma_f32_16x16x32_bf16 v[28:31], v[170:173], v[204:207], v[28:31]
	v_mfma_f32_16x16x32_bf16 v[20:23], v[180:183], v[204:207], v[20:23]
	v_mfma_f32_16x16x32_bf16 v[4:7], v[180:183], v[212:215], v[4:7]
	v_mfma_f32_16x16x32_bf16 v[12:15], v[170:173], v[212:215], v[12:15]
	s_setprio 0
	s_barrier
	s_add_i32 s18, s18, 2
	s_add_u32 s3, s3, 0x100
	s_addc_u32 s2, s2, 0
	s_add_u32 s0, s0, 0x800000
	s_addc_u32 s1, s1, 0
	s_cmp_gt_u32 s18, 13
	s_cbranch_scc0 .LBB0_478
	s_and_b64 vcc, exec, s[16:17]
	s_cbranch_vccz .LBB0_481
	s_barrier

	.amdhsa_kernel _Z14fwd_megakernel4Args
		.amdhsa_group_segment_fixed_size 0
		.amdhsa_private_segment_fixed_size 0
		.amdhsa_kernarg_size 408
		.amdhsa_user_sgpr_count 2
		.amdhsa_user_sgpr_dispatch_ptr 0
		.amdhsa_user_sgpr_queue_ptr 0
		.amdhsa_user_sgpr_kernarg_segment_ptr 1
		.amdhsa_user_sgpr_dispatch_id 0
		.amdhsa_user_sgpr_kernarg_preload_length 0
		.amdhsa_user_sgpr_kernarg_preload_offset 0
		.amdhsa_user_sgpr_private_segment_size 0
		.amdhsa_uses_dynamic_stack 0
		.amdhsa_enable_private_segment 0
		.amdhsa_system_sgpr_workgroup_id_x 1
		.amdhsa_system_sgpr_workgroup_id_y 0
		.amdhsa_system_sgpr_workgroup_id_z 0
		.amdhsa_system_sgpr_workgroup_info 0
		.amdhsa_system_vgpr_workitem_id 2
		.amdhsa_next_free_vgpr 256
		.amdhsa_next_free_sgpr 102
		.amdhsa_accum_offset 256
		.amdhsa_reserve_vcc 1
		.amdhsa_float_round_mode_32 0
		.amdhsa_float_round_mode_16_64 0
		.amdhsa_float_denorm_mode_32 3
		.amdhsa_float_denorm_mode_16_64 3
		.amdhsa_dx10_clamp 1
		.amdhsa_ieee_mode 1
		.amdhsa_fp16_overflow 0
		.amdhsa_tg_split 0
		.amdhsa_exception_fp_ieee_invalid_op 0
		.amdhsa_exception_fp_denorm_src 0
		.amdhsa_exception_fp_ieee_div_zero 0
		.amdhsa_exception_fp_ieee_overflow 0
		.amdhsa_exception_fp_ieee_underflow 0
		.amdhsa_exception_fp_ieee_inexact 0
		.amdhsa_exception_int_div_zero 0
	.end_amdhsa_kernel

.Lfunc_end0:
	.size	_Z14fwd_megakernel4Args, .Lfunc_end0-_Z14fwd_megakernel4Args
	.set _Z14fwd_megakernel4Args.num_vgpr, 256
	.set _Z14fwd_megakernel4Args.num_agpr, 0
	.set _Z14fwd_megakernel4Args.numbered_sgpr, 102
	.set _Z14fwd_megakernel4Args.num_named_barrier, 0
	.set _Z14fwd_megakernel4Args.private_seg_size, 0
	.set _Z14fwd_megakernel4Args.uses_vcc, 1
	.set _Z14fwd_megakernel4Args.uses_flat_scratch, 0
	.set _Z14fwd_megakernel4Args.has_dyn_sized_stack, 0
	.set _Z14fwd_megakernel4Args.has_recursion, 0
	.set _Z14fwd_megakernel4Args.has_indirect_call, 0

amdhsa.kernels:
  - .agpr_count:     0
    .args:
      - .offset:         0
        .size:           152
        .value_kind:     by_value
      - .offset:         152
        .size:           4
        .value_kind:     hidden_block_count_x
      - .offset:         156
        .size:           4
        .value_kind:     hidden_block_count_y
      - .offset:         160
        .size:           4
        .value_kind:     hidden_block_count_z
      - .offset:         164
        .size:           2
        .value_kind:     hidden_group_size_x
      - .offset:         166
        .size:           2
        .value_kind:     hidden_group_size_y
      - .offset:         168
        .size:           2
        .value_kind:     hidden_group_size_z
      - .offset:         170
        .size:           2
        .value_kind:     hidden_remainder_x
      - .offset:         172
        .size:           2
        .value_kind:     hidden_remainder_y
      - .offset:         174
        .size:           2
        .value_kind:     hidden_remainder_z
      - .offset:         192
        .size:           8
        .value_kind:     hidden_global_offset_x
      - .offset:         200
        .size:           8
        .value_kind:     hidden_global_offset_y
      - .offset:         208
        .size:           8
        .value_kind:     hidden_global_offset_z
      - .offset:         216
        .size:           2
        .value_kind:     hidden_grid_dims
      - .offset:         240
        .size:           8
        .value_kind:     hidden_multigrid_sync_arg
      - .offset:         272
        .size:           4
        .value_kind:     hidden_dynamic_lds_size
    .group_segment_fixed_size: 0
    .kernarg_segment_align: 8
    .kernarg_segment_size: 408
    .language:       OpenCL C
    .language_version:
      - 2
      - 0
    .max_flat_workgroup_size: 512
    .name:           _Z14fwd_megakernel4Args
    .private_segment_fixed_size: 0
    .sgpr_count:     108
    .sgpr_spill_count: 274
    .symbol:         _Z14fwd_megakernel4Args.kd
    .uniform_work_group_size: 1
    .uses_dynamic_stack: false
    .vgpr_count:     256
    .vgpr_spill_count: 0
    .wavefront_size: 64
